# v062 plus the 46 conservative s_nop 0 between the inline v_max3 pairs of the row-max chains removed
# speedup vs baseline: 1.0067x; 1.0011x over previous
; template <int MODE>
; DI void bias_init(f32x16& s0, f32x16& s1, const TP& tp, float fbm, int hi) {
; #pragma unroll
;     for (int r = 0; r < 16; ++r) {
;         const int kvc = 16 * (r >> 3) + (r & 7);
;         if (MODE == 0) { s0[r] = __builtin_fmaf(-L2E, tp.cs[kvc + 8 * hi], fbm); s1[r] = __builtin_fmaf(-L2E, tp.cs[kvc + 32 + 8 * hi], fbm); }
;         else { s0[r] = __builtin_fmaf(tp.sl, (float)kvc, fbm); s1[r] = __builtin_fmaf(tp.sl, (float)(kvc + 32), fbm); }
;     }
; }
; DI float max3_asm(float a, float b, float c) { float r; asm("v_max3_f32 %0, %1, %2, %3" : "=v"(r) : "v"(a), "v"(b), "v"(c)); return r; }
; template <bool MASK>
; DI float mask_rowmax(f32x16& s0, f32x16& s1, const TP& tp) {
;     if (MASK) {
; #pragma unroll
;         for (int r = 0; r < 16; ++r) {
;             const int kvc = 16 * (r >> 3) + (r & 7);
;             const bool v0 = tp.sel && (kvc <= tp.lim) && (kvc > tp.lim2), v1 = tp.sel && (kvc + 32 <= tp.lim) && (kvc + 32 > tp.lim2);
;             s0[r] = v0 ? s0[r] : -1e30f; s1[r] = v1 ? s1[r] : -1e30f;
;         }
;     }
;     const float seed = __builtin_fminf(s0[15], s1[15]);
;     float ma = seed, mb = seed;
; #pragma unroll
;     for (int r = 0; r < 16; r += 2) { ma = max3_asm(ma, s0[r], s1[r]); mb = max3_asm(mb, s0[r + 1], s1[r + 1]); }
;     const float mx = fmaxf(ma, mb);
;     return fmaxf(mx, __shfl_xor(mx, 32));
; }
; template <int MODE, bool MASK, bool WITH_O>
; DI void attn_tile_t(lptr Kt, lptr Vt, const bf16x8 (&qf)[4], f32x16& o0, f32x16& o1, RowState& rs, const TP& tp, int lane) {
;     const int hi = lane >> 5;
;     f32x16 s0, s1;
;     bias_init<MODE>(s0, s1, tp, tp.fb - rs.mref, hi);
;     qk_acc(Kt, qf, s0, s1, lane);
;     const float mx = mask_rowmax<MASK>(s0, s1, tp);
;     const bool was = rs.seen; rs.seen = was || (mx > -1e29f);
;     const bool trig = (mx > 8.f) || (!was && mx > -1e29f && mx < -8.f);
;     if (__builtin_expect(__any(trig), 0)) {
.LBB0_493:
	s_lshl_b32 s2, s55, 8
	s_add_i32 s26, s2, 0
	s_mul_i32 s2, s55, 0x2300
	s_add_i32 s56, s26, s2
	s_mov_b64 s[2:3], -1
	s_cmp_le_i32 s31, s42
	v_sub_f32_e32 v156, v157, v160
	v_add3_u32 v161, s56, v131, v133
	v_lshl_add_u32 v162, v126, 2, s26
	s_cbranch_scc0 .LBB0_498
	ds_read_b128 v[34:37], v162 offset:36992
	ds_read_b128 v[38:41], v162 offset:36864
	ds_read_b128 v[42:45], v162 offset:36880
	ds_read_b128 v[46:49], v162 offset:37008
	ds_read_b128 v[50:53], v162 offset:36928
	ds_read_b128 v[54:57], v162 offset:37056
	ds_read_b128 v[58:61], v162 offset:36944
	ds_read_b128 v[62:65], v162 offset:37072
	ds_read_b128 v[166:169], v161 offset:4608
	ds_read_b128 v[216:219], v161
	ds_read_b128 v[228:231], v161 offset:32
	ds_read_b128 v[232:235], v161 offset:4640
	ds_read_b128 v[236:239], v161 offset:64
	ds_read_b128 v[240:243], v161 offset:4672
	ds_read_b128 v[244:247], v161 offset:96
	ds_read_b128 v[252:255], v161 offset:4704
	s_waitcnt lgkmcnt(13)
	v_pk_fma_f32 v[88:89], v[44:45], s[80:81], v[156:157] op_sel_hi:[1,0,0]
	s_waitcnt lgkmcnt(11)
	v_pk_fma_f32 v[92:93], v[52:53], s[80:81], v[156:157] op_sel_hi:[1,0,0]
	v_pk_fma_f32 v[84:85], v[40:41], s[80:81], v[156:157] op_sel_hi:[1,0,0]
	s_waitcnt lgkmcnt(9)
	v_pk_fma_f32 v[96:97], v[60:61], s[80:81], v[156:157] op_sel_hi:[1,0,0]
	v_pk_fma_f32 v[94:95], v[58:59], s[80:81], v[156:157] op_sel_hi:[1,0,0]
	v_pk_fma_f32 v[90:91], v[50:51], s[80:81], v[156:157] op_sel_hi:[1,0,0]
	v_pk_fma_f32 v[86:87], v[42:43], s[80:81], v[156:157] op_sel_hi:[1,0,0]
	v_pk_fma_f32 v[82:83], v[38:39], s[80:81], v[156:157] op_sel_hi:[1,0,0]
	s_waitcnt lgkmcnt(8)
	v_pk_fma_f32 v[80:81], v[64:65], s[80:81], v[156:157] op_sel_hi:[1,0,0]
	v_pk_fma_f32 v[76:77], v[56:57], s[80:81], v[156:157] op_sel_hi:[1,0,0]
	v_pk_fma_f32 v[72:73], v[48:49], s[80:81], v[156:157] op_sel_hi:[1,0,0]
	v_pk_fma_f32 v[68:69], v[36:37], s[80:81], v[156:157] op_sel_hi:[1,0,0]
	v_pk_fma_f32 v[78:79], v[62:63], s[80:81], v[156:157] op_sel_hi:[1,0,0]
	v_pk_fma_f32 v[74:75], v[54:55], s[80:81], v[156:157] op_sel_hi:[1,0,0]
	v_pk_fma_f32 v[70:71], v[46:47], s[80:81], v[156:157] op_sel_hi:[1,0,0]
	v_pk_fma_f32 v[66:67], v[34:35], s[80:81], v[156:157] op_sel_hi:[1,0,0]
	s_setprio 1
	s_waitcnt lgkmcnt(6)
	v_mfma_f32_32x32x16_bf16 v[82:97], v[216:219], v[98:101], v[82:97]
	v_mfma_f32_32x32x16_bf16 v[66:81], v[166:169], v[98:101], v[66:81]
	s_waitcnt lgkmcnt(5)
	v_mfma_f32_32x32x16_bf16 v[82:97], v[228:231], v[102:105], v[82:97]
	s_waitcnt lgkmcnt(4)
	v_mfma_f32_32x32x16_bf16 v[66:81], v[232:235], v[102:105], v[66:81]
	s_waitcnt lgkmcnt(3)
	v_mfma_f32_32x32x16_bf16 v[82:97], v[236:239], v[106:109], v[82:97]
	s_waitcnt lgkmcnt(2)
	v_mfma_f32_32x32x16_bf16 v[66:81], v[240:243], v[106:109], v[66:81]
	s_waitcnt lgkmcnt(1)
	v_mfma_f32_32x32x16_bf16 v[82:97], v[244:247], v[110:113], v[82:97]
	s_waitcnt lgkmcnt(0)
	v_mfma_f32_32x32x16_bf16 v[66:81], v[252:255], v[110:113], v[66:81]
	s_setprio 0
	v_add3_u32 v228, s56, v135, v141
	ds_read_b128 v[216:219], v228 offset:18432
	ds_read_b128 v[38:41], v228 offset:23040
	ds_read_b128 v[42:45], v228 offset:18464
	ds_read_b128 v[46:49], v228 offset:23072
	ds_read_b128 v[50:53], v228 offset:18496
	ds_read_b128 v[54:57], v228 offset:23104
	ds_read_b128 v[58:61], v228 offset:18528
	ds_read_b128 v[62:65], v228 offset:23136
	s_nop 1
	v_max_f32_e32 v34, v81, v81
	v_max_f32_e32 v35, v97, v97
	v_min_f32_e32 v34, v35, v34
	v_max3_f32 v35, v34, v82, v66
	v_max3_f32 v34, v34, v83, v67
	v_and_b32_e32 v36, 64, v209
	v_max3_f32 v35, v35, v84, v68
	v_max3_f32 v34, v34, v85, v69
	v_add_u32_e32 v36, 64, v36
	v_max3_f32 v35, v35, v86, v70
	v_max3_f32 v34, v34, v87, v71
	s_mov_b32 s2, 0xefa18f08
	v_max3_f32 v35, v35, v88, v72
	v_max3_f32 v34, v34, v89, v73
	s_mov_b64 s[28:29], -1
	v_max3_f32 v35, v35, v90, v74
	v_max3_f32 v34, v34, v91, v75
	v_max3_f32 v35, v35, v92, v76
	v_max3_f32 v34, v34, v93, v77
	v_max3_f32 v35, v35, v94, v78
	v_max3_f32 v34, v34, v95, v79
	v_max3_f32 v35, v35, v96, v80
	v_max3_f32 v34, v34, v97, v81
	v_max_f32_e32 v34, v34, v34
	v_max_f32_e32 v35, v35, v35
	v_max_f32_e32 v34, v35, v34
	v_mov_b32_e32 v35, v34
	s_nop 1
	v_permlane32_swap_b32_e32 v35, v34
	s_waitcnt lgkmcnt(0)
	v_max_f32_e32 v165, v34, v35
	v_cmp_lt_f32_e64 s[26:27], s2, v165
	s_mov_b32 s2, 0x41000000
	v_cmp_lt_f32_e32 vcc, s2, v165
	s_mov_b32 s28, 0xc1000000
	v_cmp_gt_f32_e64 s[28:29], s28, v165
	s_and_b64 s[28:29], s[28:29], s[26:27]
	s_andn2_b64 s[28:29], s[28:29], s[22:23]
	s_or_b64 s[28:29], s[28:29], vcc
	s_and_b64 vcc, exec, s[28:29]
	v_mov_b32_e32 v163, v160
	v_mov_b32_e32 v164, v159
	s_cbranch_vccnz .LBB0_514

; #define LAS __attribute__((address_space(3)))
; #define MFMA32(a, b, c) __builtin_amdgcn_mfma_f32_32x32x16_bf16((a), (b), (c), 0, 0, 0)
; DI void qk_acc(lptr Kt, const bf16x8 (&qf)[4], f32x16& s0, f32x16& s1, int lane) {
;     const int i = lane & 31, hi = lane >> 5;
;     const int krow = (i & 19) | ((i & 4) << 1) | ((i & 8) >> 1);
;     lptr kp = Kt + krow * KPB + hi * 16;
;     bf16x8 a0[4], a1[4];
; #pragma unroll
;     for (int d0 = 0; d0 < 4; ++d0) { a0[d0] = *(LAS bf16x8*)(kp + d0 * 32); a1[d0] = *(LAS bf16x8*)(kp + 32 * KPB + d0 * 32); }
;     __builtin_amdgcn_s_setprio(1);
; #pragma unroll
;     for (int d0 = 0; d0 < 4; ++d0) { s0 = MFMA32(a0[d0], qf[d0], s0); s1 = MFMA32(a1[d0], qf[d0], s1); }
;     __builtin_amdgcn_s_setprio(0);
; template <int MODE>
; DI void bias_init(f32x16& s0, f32x16& s1, const TP& tp, float fbm, int hi) {
; #pragma unroll
;     for (int r = 0; r < 16; ++r) {
;         const int kvc = 16 * (r >> 3) + (r & 7);
;         if (MODE == 0) { s0[r] = __builtin_fmaf(-L2E, tp.cs[kvc + 8 * hi], fbm); s1[r] = __builtin_fmaf(-L2E, tp.cs[kvc + 32 + 8 * hi], fbm); }
;         else { s0[r] = __builtin_fmaf(tp.sl, (float)kvc, fbm); s1[r] = __builtin_fmaf(tp.sl, (float)(kvc + 32), fbm); }
;     }
; }
; DI float max3_asm(float a, float b, float c) { float r; asm("v_max3_f32 %0, %1, %2, %3" : "=v"(r) : "v"(a), "v"(b), "v"(c)); return r; }
; template <bool MASK>
; DI float mask_rowmax(f32x16& s0, f32x16& s1, const TP& tp) {
;     if (MASK) {
; #pragma unroll
;         for (int r = 0; r < 16; ++r) {
;             const int kvc = 16 * (r >> 3) + (r & 7);
;             const bool v0 = tp.sel && (kvc <= tp.lim) && (kvc > tp.lim2), v1 = tp.sel && (kvc + 32 <= tp.lim) && (kvc + 32 > tp.lim2);
;             s0[r] = v0 ? s0[r] : -1e30f; s1[r] = v1 ? s1[r] : -1e30f;
;         }
;     }
;     const float seed = __builtin_fminf(s0[15], s1[15]);
;     float ma = seed, mb = seed;
; #pragma unroll
;     for (int r = 0; r < 16; r += 2) { ma = max3_asm(ma, s0[r], s1[r]); mb = max3_asm(mb, s0[r + 1], s1[r + 1]); }
;     const float mx = fmaxf(ma, mb);
;     return fmaxf(mx, __shfl_xor(mx, 32));
; }
.LBB0_498:
	s_and_b64 vcc, exec, s[2:3]
	s_cbranch_vccz .LBB0_503
	s_nop 8
	ds_read_b128 v[50:53], v162 offset:36992
	ds_read_b128 v[34:37], v162 offset:36864
	ds_read_b128 v[38:41], v162 offset:36880
	ds_read_b128 v[54:57], v162 offset:37008
	ds_read_b128 v[42:45], v162 offset:36928
	ds_read_b128 v[58:61], v162 offset:37056
	ds_read_b128 v[46:49], v162 offset:36944
	ds_read_b128 v[62:65], v162 offset:37072
	ds_read_b128 v[66:69], v161 offset:4608
	ds_read_b128 v[70:73], v161
	ds_read_b128 v[74:77], v161 offset:32
	ds_read_b128 v[78:81], v161 offset:4640
	ds_read_b128 v[82:85], v161 offset:64
	ds_read_b128 v[86:89], v161 offset:4672
	ds_read_b128 v[90:93], v161 offset:96
	ds_read_b128 v[94:97], v161 offset:4704
	s_waitcnt lgkmcnt(11)
	v_pk_fma_f32 v[44:45], v[44:45], s[80:81], v[156:157] op_sel_hi:[1,0,0]
	v_pk_fma_f32 v[40:41], v[40:41], s[80:81], v[156:157] op_sel_hi:[1,0,0]
	v_pk_fma_f32 v[36:37], v[36:37], s[80:81], v[156:157] op_sel_hi:[1,0,0]
	s_waitcnt lgkmcnt(9)
	v_pk_fma_f32 v[46:47], v[46:47], s[80:81], v[156:157] op_sel_hi:[1,0,0]
	v_pk_fma_f32 v[42:43], v[42:43], s[80:81], v[156:157] op_sel_hi:[1,0,0]
	v_pk_fma_f32 v[38:39], v[38:39], s[80:81], v[156:157] op_sel_hi:[1,0,0]
	v_pk_fma_f32 v[34:35], v[34:35], s[80:81], v[156:157] op_sel_hi:[1,0,0]
	v_pk_fma_f32 v[56:57], v[56:57], s[80:81], v[156:157] op_sel_hi:[1,0,0]
	v_pk_fma_f32 v[52:53], v[52:53], s[80:81], v[156:157] op_sel_hi:[1,0,0]
	v_pk_fma_f32 v[54:55], v[54:55], s[80:81], v[156:157] op_sel_hi:[1,0,0]
	v_pk_fma_f32 v[50:51], v[50:51], s[80:81], v[156:157] op_sel_hi:[1,0,0]
	v_pk_fma_f32 v[48:49], v[48:49], s[80:81], v[156:157] op_sel_hi:[1,0,0]
	s_waitcnt lgkmcnt(8)
	v_pk_fma_f32 v[64:65], v[64:65], s[80:81], v[156:157] op_sel_hi:[1,0,0]
	v_pk_fma_f32 v[60:61], v[60:61], s[80:81], v[156:157] op_sel_hi:[1,0,0]
	v_pk_fma_f32 v[62:63], v[62:63], s[80:81], v[156:157] op_sel_hi:[1,0,0]
	v_pk_fma_f32 v[58:59], v[58:59], s[80:81], v[156:157] op_sel_hi:[1,0,0]
	s_setprio 1
	s_waitcnt lgkmcnt(6)
	v_mfma_f32_32x32x16_bf16 v[34:49], v[70:73], v[98:101], v[34:49]
	v_mfma_f32_32x32x16_bf16 v[50:65], v[66:69], v[98:101], v[50:65]
	s_waitcnt lgkmcnt(5)
	v_mfma_f32_32x32x16_bf16 v[34:49], v[74:77], v[102:105], v[34:49]
	s_waitcnt lgkmcnt(4)
	v_mfma_f32_32x32x16_bf16 v[50:65], v[78:81], v[102:105], v[50:65]
	s_waitcnt lgkmcnt(3)
	v_mfma_f32_32x32x16_bf16 v[34:49], v[82:85], v[106:109], v[34:49]
	s_waitcnt lgkmcnt(2)
	v_mfma_f32_32x32x16_bf16 v[50:65], v[86:89], v[106:109], v[50:65]
	s_waitcnt lgkmcnt(1)
	v_mfma_f32_32x32x16_bf16 v[34:49], v[90:93], v[110:113], v[34:49]
	s_waitcnt lgkmcnt(0)
	v_mfma_f32_32x32x16_bf16 v[50:65], v[94:97], v[110:113], v[50:65]
	s_setprio 0
	v_cmp_lt_i32_e32 vcc, 0, v158
	s_mov_b32 s2, 0xefa18f08
	s_nop 6
	v_cndmask_b32_e32 v72, v210, v35, vcc
	v_cmp_lt_i32_e64 s[98:99], -1, v158
	v_cmp_lt_i32_e64 s[100:101], 32, v158
	v_cmp_lt_i32_e32 vcc, 31, v158
	v_cndmask_b32_e64 v76, v210, v34, s[98:99]
	v_cndmask_b32_e64 v66, v210, v51, s[100:101]
	v_cndmask_b32_e32 v68, v210, v50, vcc
	v_cmp_lt_i32_e64 s[98:99], 2, v158
	v_cmp_lt_i32_e64 s[100:101], 1, v158
	v_cmp_lt_i32_e32 vcc, 34, v158
	v_cndmask_b32_e64 v71, v210, v37, s[98:99]
	v_cndmask_b32_e64 v75, v210, v36, s[100:101]
	v_cndmask_b32_e32 v53, v210, v53, vcc
	v_cmp_lt_i32_e64 s[98:99], 33, v158
	v_cmp_lt_i32_e64 s[100:101], 4, v158
	v_cmp_lt_i32_e32 vcc, 3, v158
	v_cndmask_b32_e64 v67, v210, v52, s[98:99]
	v_cndmask_b32_e64 v70, v210, v39, s[100:101]
	v_cndmask_b32_e32 v74, v210, v38, vcc
	v_cmp_lt_i32_e64 s[98:99], 36, v158
	v_cmp_lt_i32_e64 s[100:101], 35, v158
	v_cmp_lt_i32_e32 vcc, 6, v158
	v_cndmask_b32_e64 v51, v210, v55, s[98:99]
	v_cndmask_b32_e64 v54, v210, v54, s[100:101]
	v_cndmask_b32_e32 v69, v210, v41, vcc
	v_cmp_lt_i32_e64 s[98:99], 5, v158
	v_cmp_lt_i32_e64 s[100:101], 38, v158
	v_cmp_lt_i32_e32 vcc, 37, v158
	v_cndmask_b32_e64 v73, v210, v40, s[98:99]
	v_cndmask_b32_e64 v50, v210, v57, s[100:101]
	v_cndmask_b32_e32 v52, v210, v56, vcc
	v_cmp_lt_i32_e64 s[98:99], 16, v158
	v_cmp_lt_i32_e64 s[100:101], 15, v158
	v_cmp_lt_i32_e32 vcc, 48, v158
	v_cndmask_b32_e64 v55, v210, v43, s[98:99]
	v_cndmask_b32_e64 v57, v210, v42, s[100:101]
	v_cndmask_b32_e32 v38, v210, v59, vcc
	v_cmp_lt_i32_e64 s[98:99], 47, v158
	v_cmp_lt_i32_e64 s[100:101], 18, v158
	v_cmp_lt_i32_e32 vcc, 17, v158
	v_cndmask_b32_e64 v41, v210, v58, s[98:99]
	v_cndmask_b32_e64 v45, v210, v45, s[100:101]
	v_cndmask_b32_e32 v56, v210, v44, vcc
	v_cmp_lt_i32_e64 s[98:99], 50, v158
	v_cmp_lt_i32_e64 s[100:101], 49, v158
	v_cmp_lt_i32_e32 vcc, 20, v158
	v_cndmask_b32_e64 v36, v210, v61, s[98:99]
	v_cndmask_b32_e64 v40, v210, v60, s[100:101]
	v_cndmask_b32_e32 v43, v210, v47, vcc
	v_cmp_lt_i32_e64 s[98:99], 19, v158
	v_cmp_lt_i32_e64 s[100:101], 52, v158
	v_cmp_lt_i32_e32 vcc, 51, v158
	v_cndmask_b32_e64 v46, v210, v46, s[98:99]
	v_cndmask_b32_e64 v35, v210, v63, s[100:101]
	v_cndmask_b32_e32 v39, v210, v62, vcc
	v_cmp_lt_i32_e32 vcc, 22, v158
	s_nop 1
	v_cndmask_b32_e32 v42, v210, v49, vcc
	v_cmp_lt_i32_e32 vcc, 21, v158
	v_and_b32_e32 v49, 64, v209
	v_add_u32_e32 v49, 64, v49
	v_cndmask_b32_e32 v44, v210, v48, vcc
	v_cmp_lt_i32_e32 vcc, 54, v158
	v_max_f32_e32 v48, v42, v42
	s_nop 0
	v_cndmask_b32_e32 v34, v210, v65, vcc
	v_max_f32_e32 v47, v34, v34
	v_min_f32_e32 v47, v48, v47
	v_max3_f32 v48, v47, v76, v68
	v_max3_f32 v47, v47, v72, v66
	v_cmp_lt_i32_e32 vcc, 53, v158
	v_max3_f32 v48, v48, v75, v67
	v_max3_f32 v47, v47, v71, v53
	v_max3_f32 v48, v48, v74, v54
	v_max3_f32 v47, v47, v70, v51
	s_nop 0
	v_cndmask_b32_e32 v37, v210, v64, vcc
	v_max3_f32 v48, v48, v73, v52
	v_max3_f32 v47, v47, v69, v50
	v_max3_f32 v48, v48, v57, v41
	v_max3_f32 v47, v47, v55, v38
	v_max3_f32 v48, v48, v56, v40
	v_max3_f32 v47, v47, v45, v36
	v_max3_f32 v48, v48, v46, v39
	v_max3_f32 v47, v47, v43, v35
	v_max3_f32 v48, v48, v44, v37
	v_max3_f32 v47, v47, v42, v34
	v_max_f32_e32 v47, v47, v47
	v_max_f32_e32 v48, v48, v48
	v_max_f32_e32 v47, v48, v47
	v_mov_b32_e32 v48, v47
	s_nop 1
	v_permlane32_swap_b32_e32 v48, v47
	s_waitcnt lgkmcnt(0)
	v_max_f32_e32 v47, v47, v48
	v_cmp_lt_f32_e64 s[26:27], s2, v47
	s_mov_b32 s2, 0x41000000
	v_cmp_lt_f32_e32 vcc, s2, v47
	s_mov_b32 s2, 0xc1000000
	v_cmp_gt_f32_e64 s[2:3], s2, v47
	s_and_b64 s[2:3], s[2:3], s[26:27]
	s_andn2_b64 s[2:3], s[2:3], s[22:23]
	s_or_b64 s[2:3], s[2:3], vcc
	s_and_b64 vcc, exec, s[2:3]
	s_cbranch_vccnz .LBB0_515

; template <int MODE>
; DI void bias_init(f32x16& s0, f32x16& s1, const TP& tp, float fbm, int hi) {
; #pragma unroll
;     for (int r = 0; r < 16; ++r) {
;         const int kvc = 16 * (r >> 3) + (r & 7);
;         if (MODE == 0) { s0[r] = __builtin_fmaf(-L2E, tp.cs[kvc + 8 * hi], fbm); s1[r] = __builtin_fmaf(-L2E, tp.cs[kvc + 32 + 8 * hi], fbm); }
;         else { s0[r] = __builtin_fmaf(tp.sl, (float)kvc, fbm); s1[r] = __builtin_fmaf(tp.sl, (float)(kvc + 32), fbm); }
;     }
; }
; DI float max3_asm(float a, float b, float c) { float r; asm("v_max3_f32 %0, %1, %2, %3" : "=v"(r) : "v"(a), "v"(b), "v"(c)); return r; }
; template <bool MASK>
; DI float mask_rowmax(f32x16& s0, f32x16& s1, const TP& tp) {
;     if (MASK) {
; #pragma unroll
;         for (int r = 0; r < 16; ++r) {
;             const int kvc = 16 * (r >> 3) + (r & 7);
;             const bool v0 = tp.sel && (kvc <= tp.lim) && (kvc > tp.lim2), v1 = tp.sel && (kvc + 32 <= tp.lim) && (kvc + 32 > tp.lim2);
;             s0[r] = v0 ? s0[r] : -1e30f; s1[r] = v1 ? s1[r] : -1e30f;
;         }
;     }
;     const float seed = __builtin_fminf(s0[15], s1[15]);
;     float ma = seed, mb = seed;
; #pragma unroll
;     for (int r = 0; r < 16; r += 2) { ma = max3_asm(ma, s0[r], s1[r]); mb = max3_asm(mb, s0[r + 1], s1[r + 1]); }
;     const float mx = fmaxf(ma, mb);
;     return fmaxf(mx, __shfl_xor(mx, 32));
; }
; template <int MODE, bool MASK, bool WITH_O>
; DI void attn_tile_t(lptr Kt, lptr Vt, const bf16x8 (&qf)[4], f32x16& o0, f32x16& o1, RowState& rs, const TP& tp, int lane) {
;     const int hi = lane >> 5;
;     f32x16 s0, s1;
;     bias_init<MODE>(s0, s1, tp, tp.fb - rs.mref, hi);
;     qk_acc(Kt, qf, s0, s1, lane);
;     const float mx = mask_rowmax<MASK>(s0, s1, tp);
;     const bool was = rs.seen; rs.seen = was || (mx > -1e29f);
;     const bool trig = (mx > 8.f) || (!was && mx > -1e29f && mx < -8.f);
; DI void cmpwin_unit(const Params& P, lptr L, int u, int tid, int lane, int wid) {
;     ...
;             const int n0 = jt * 64;
;             TP tp; tp.cs = nullptr; tp.sl = 16.f * sl; tp.fb = sl * (float)(16 * (n0 + 8 * hi) + 31 - t); tp.lim = nlim - n0 - 8 * hi; tp.lim2 = -(1 << 30); tp.sel = true;
;             if (n0 + 63 <= nfull) attn_tile_t<1, false, false>(Kt, Vt, qf, od0, od1, rs, tp, lane);
.LBB0_526:
	v_cvt_f32_i32_e32 v2, v47
	s_and_b32 s43, s30, 1
	s_mul_i32 s2, s43, 0x2400
	s_add_i32 s52, s2, 0
	v_mul_f32_e32 v50, v150, v2
	s_cmp_gt_i32 s42, s29
	s_mov_b64 s[2:3], -1
	s_cbranch_scc1 .LBB0_535
	s_mov_b32 s2, 2.0
	v_sub_f32_e32 v2, v50, v49
	s_mov_b32 s3, 0x40400000
	v_add3_u32 v51, s52, v131, v133
	v_pk_fma_f32 v[20:21], v[80:81], s[2:3], v[2:3] op_sel_hi:[1,1,0]
	s_mov_b32 s2, 4.0
	ds_read_b128 v[52:55], v51 offset:4608
	ds_read_b128 v[56:59], v51
	ds_read_b128 v[60:63], v51 offset:32
	ds_read_b128 v[64:67], v51 offset:4640
	ds_read_b128 v[68:71], v51 offset:64
	ds_read_b128 v[88:91], v51 offset:4672
	ds_read_b128 v[92:95], v51 offset:96
	ds_read_b128 v[114:117], v51 offset:4704
	s_mov_b32 s3, 0x40a00000
	v_pk_fma_f32 v[22:23], v[80:81], s[2:3], v[2:3] op_sel_hi:[1,1,0]
	s_mov_b32 s2, 0x40c00000
	s_mov_b32 s3, 0x40e00000
	v_pk_fma_f32 v[24:25], v[80:81], s[2:3], v[2:3] op_sel_hi:[1,1,0]
	s_mov_b32 s2, 0x41800000
	s_mov_b32 s3, 0x41880000
	v_pk_fma_f32 v[26:27], v[80:81], s[2:3], v[2:3] op_sel_hi:[1,1,0]
	s_mov_b32 s2, 0x41900000
	s_mov_b32 s3, 0x41980000
	v_pk_fma_f32 v[28:29], v[80:81], s[2:3], v[2:3] op_sel_hi:[1,1,0]
	s_mov_b32 s2, 0x41a00000
	s_mov_b32 s3, 0x41a80000
	v_mov_b32_e32 v79, v78
	v_fma_f32 v18, 0, v78, v2
	v_add_f32_e32 v19, v78, v2
	v_pk_fma_f32 v[30:31], v[80:81], s[2:3], v[2:3] op_sel_hi:[1,1,0]
	v_pk_fma_f32 v[32:33], v[80:81], s[18:19], v[2:3] op_sel_hi:[1,1,0]
	v_pk_fma_f32 v[16:17], v[78:79], s[4:5], v[2:3] op_sel_hi:[1,1,0]
	v_pk_fma_f32 v[14:15], v[78:79], s[14:15], v[2:3] op_sel_hi:[1,1,0]
	v_pk_fma_f32 v[12:13], v[78:79], s[16:17], v[2:3] op_sel_hi:[1,1,0]
	v_pk_fma_f32 v[10:11], v[78:79], s[94:95], v[2:3] op_sel_hi:[1,1,0]
	v_pk_fma_f32 v[8:9], v[78:79], s[96:97], v[2:3] op_sel_hi:[1,1,0]
	v_pk_fma_f32 v[6:7], v[78:79], s[84:85], v[2:3] op_sel_hi:[1,1,0]
	v_pk_fma_f32 v[4:5], v[78:79], s[72:73], v[2:3] op_sel_hi:[1,1,0]
	v_pk_fma_f32 v[2:3], v[82:83], s[44:45], v[2:3] op_sel_hi:[1,1,0]
	s_setprio 1
	s_waitcnt vmcnt(4) lgkmcnt(6)
	v_mfma_f32_32x32x16_bf16 v[18:33], v[56:59], v[98:101], v[18:33]
	v_mfma_f32_32x32x16_bf16 v[2:17], v[52:55], v[98:101], v[2:17]
	s_waitcnt vmcnt(3) lgkmcnt(5)
	v_mfma_f32_32x32x16_bf16 v[18:33], v[60:63], v[102:105], v[18:33]
	s_waitcnt lgkmcnt(4)
	v_mfma_f32_32x32x16_bf16 v[2:17], v[64:67], v[102:105], v[2:17]
	s_waitcnt vmcnt(2) lgkmcnt(3)
	v_mfma_f32_32x32x16_bf16 v[18:33], v[68:71], v[106:109], v[18:33]
	s_waitcnt lgkmcnt(2)
	v_mfma_f32_32x32x16_bf16 v[2:17], v[88:91], v[106:109], v[2:17]
	s_waitcnt vmcnt(1) lgkmcnt(1)
	v_mfma_f32_32x32x16_bf16 v[18:33], v[92:95], v[110:113], v[18:33]
	s_waitcnt lgkmcnt(0)
	v_mfma_f32_32x32x16_bf16 v[2:17], v[114:117], v[110:113], v[2:17]
	s_setprio 0
	s_nop 10
	v_max_f32_e32 v51, v17, v17
	v_max_f32_e32 v52, v33, v33
	v_min_f32_e32 v51, v52, v51
	v_max3_f32 v52, v51, v18, v2
	v_max3_f32 v51, v51, v19, v3
	v_and_b32_e32 v53, 64, v209
	v_max3_f32 v52, v52, v20, v4
	v_max3_f32 v51, v51, v21, v5
	v_add_u32_e32 v53, 64, v53
	v_max3_f32 v52, v52, v22, v6
	v_max3_f32 v51, v51, v23, v7
	s_mov_b32 s2, 0xefa18f08
	v_max3_f32 v52, v52, v24, v8
	v_max3_f32 v51, v51, v25, v9
	s_mov_b64 s[26:27], -1
	v_max3_f32 v52, v52, v26, v10
	v_max3_f32 v51, v51, v27, v11
	v_max3_f32 v52, v52, v28, v12
	v_max3_f32 v51, v51, v29, v13
	v_max3_f32 v52, v52, v30, v14
	v_max3_f32 v51, v51, v31, v15
	v_max3_f32 v52, v52, v32, v16
	v_max3_f32 v51, v51, v33, v17
	v_max_f32_e32 v51, v51, v51
	v_max_f32_e32 v52, v52, v52
	v_max_f32_e32 v51, v52, v51
	v_mov_b32_e32 v52, v51
	s_nop 1
	v_permlane32_swap_b32_e32 v52, v51
	s_waitcnt lgkmcnt(0)
	v_max_f32_e32 v53, v51, v52
	v_cmp_lt_f32_e64 s[24:25], s2, v53
	s_mov_b32 s2, 0x41000000
	v_cmp_lt_f32_e32 vcc, s2, v53
	s_mov_b32 s26, 0xc1000000
	v_cmp_gt_f32_e64 s[26:27], s26, v53
	s_and_b64 s[26:27], s[26:27], s[24:25]
	s_andn2_b64 s[26:27], s[26:27], s[0:1]
	s_or_b64 s[26:27], s[26:27], vcc
	s_and_b64 vcc, exec, s[26:27]
	v_mov_b32_e32 v51, v49
	v_mov_b32_e32 v52, v46
	s_cbranch_vccnz .LBB0_540

; #define LAS __attribute__((address_space(3)))
; #define MFMA32(a, b, c) __builtin_amdgcn_mfma_f32_32x32x16_bf16((a), (b), (c), 0, 0, 0)
; DI void qk_acc(lptr Kt, const bf16x8 (&qf)[4], f32x16& s0, f32x16& s1, int lane) {
;     const int i = lane & 31, hi = lane >> 5;
;     const int krow = (i & 19) | ((i & 4) << 1) | ((i & 8) >> 1);
;     lptr kp = Kt + krow * KPB + hi * 16;
;     bf16x8 a0[4], a1[4];
; #pragma unroll
;     for (int d0 = 0; d0 < 4; ++d0) { a0[d0] = *(LAS bf16x8*)(kp + d0 * 32); a1[d0] = *(LAS bf16x8*)(kp + 32 * KPB + d0 * 32); }
;     __builtin_amdgcn_s_setprio(1);
; #pragma unroll
;     for (int d0 = 0; d0 < 4; ++d0) { s0 = MFMA32(a0[d0], qf[d0], s0); s1 = MFMA32(a1[d0], qf[d0], s1); }
;     __builtin_amdgcn_s_setprio(0);
; template <int MODE>
; DI void bias_init(f32x16& s0, f32x16& s1, const TP& tp, float fbm, int hi) {
; #pragma unroll
;     for (int r = 0; r < 16; ++r) {
;         const int kvc = 16 * (r >> 3) + (r & 7);
;         if (MODE == 0) { s0[r] = __builtin_fmaf(-L2E, tp.cs[kvc + 8 * hi], fbm); s1[r] = __builtin_fmaf(-L2E, tp.cs[kvc + 32 + 8 * hi], fbm); }
;         else { s0[r] = __builtin_fmaf(tp.sl, (float)kvc, fbm); s1[r] = __builtin_fmaf(tp.sl, (float)(kvc + 32), fbm); }
;     }
; }
; DI float max3_asm(float a, float b, float c) { float r; asm("v_max3_f32 %0, %1, %2, %3" : "=v"(r) : "v"(a), "v"(b), "v"(c)); return r; }
; template <bool MASK>
; DI float mask_rowmax(f32x16& s0, f32x16& s1, const TP& tp) {
;     if (MASK) {
; #pragma unroll
;         for (int r = 0; r < 16; ++r) {
;             const int kvc = 16 * (r >> 3) + (r & 7);
;             const bool v0 = tp.sel && (kvc <= tp.lim) && (kvc > tp.lim2), v1 = tp.sel && (kvc + 32 <= tp.lim) && (kvc + 32 > tp.lim2);
;             s0[r] = v0 ? s0[r] : -1e30f; s1[r] = v1 ? s1[r] : -1e30f;
;         }
;     }
;     const float seed = __builtin_fminf(s0[15], s1[15]);
;     float ma = seed, mb = seed;
; #pragma unroll
;     for (int r = 0; r < 16; r += 2) { ma = max3_asm(ma, s0[r], s1[r]); mb = max3_asm(mb, s0[r + 1], s1[r + 1]); }
;     const float mx = fmaxf(ma, mb);
;     return fmaxf(mx, __shfl_xor(mx, 32));
; }
.LBB0_535:
	s_and_b64 vcc, exec, s[2:3]
	s_cbranch_vccz .LBB0_531
	v_sub_f32_e32 v18, v50, v49
	v_add3_u32 v232, s52, v131, v133
	ds_read_b128 v[50:53], v232 offset:4608
	ds_read_b128 v[54:57], v232
	ds_read_b128 v[58:61], v232 offset:32
	ds_read_b128 v[62:65], v232 offset:4640
	ds_read_b128 v[66:69], v232 offset:64
	ds_read_b128 v[70:73], v232 offset:4672
	ds_read_b128 v[88:91], v232 offset:96
	ds_read_b128 v[92:95], v232 offset:4704
	s_mov_b32 s2, 2.0
	v_mov_b32_e32 v79, v78
	s_mov_b32 s3, 0x40400000
	v_pk_fma_f32 v[32:33], v[78:79], s[4:5], v[18:19] op_sel_hi:[1,1,0]
	v_pk_fma_f32 v[30:31], v[78:79], s[14:15], v[18:19] op_sel_hi:[1,1,0]
	v_pk_fma_f32 v[28:29], v[78:79], s[16:17], v[18:19] op_sel_hi:[1,1,0]
	v_pk_fma_f32 v[26:27], v[78:79], s[94:95], v[18:19] op_sel_hi:[1,1,0]
	v_pk_fma_f32 v[24:25], v[78:79], s[96:97], v[18:19] op_sel_hi:[1,1,0]
	v_pk_fma_f32 v[22:23], v[78:79], s[84:85], v[18:19] op_sel_hi:[1,1,0]
	v_pk_fma_f32 v[20:21], v[78:79], s[72:73], v[18:19] op_sel_hi:[1,1,0]
	v_pk_fma_f32 v[4:5], v[80:81], s[2:3], v[18:19] op_sel_hi:[1,1,0]
	s_mov_b32 s2, 4.0
	s_mov_b32 s3, 0x40a00000
	v_pk_fma_f32 v[6:7], v[80:81], s[2:3], v[18:19] op_sel_hi:[1,1,0]
	s_mov_b32 s2, 0x40c00000
	s_mov_b32 s3, 0x40e00000
	v_pk_fma_f32 v[8:9], v[80:81], s[2:3], v[18:19] op_sel_hi:[1,1,0]
	s_mov_b32 s2, 0x41800000
	s_mov_b32 s3, 0x41880000
	v_pk_fma_f32 v[10:11], v[80:81], s[2:3], v[18:19] op_sel_hi:[1,1,0]
	s_mov_b32 s2, 0x41900000
	s_mov_b32 s3, 0x41980000
	v_pk_fma_f32 v[12:13], v[80:81], s[2:3], v[18:19] op_sel_hi:[1,1,0]
	s_mov_b32 s2, 0x41a00000
	s_mov_b32 s3, 0x41a80000
	v_fma_f32 v2, 0, v78, v18
	v_add_f32_e32 v3, v78, v18
	v_pk_fma_f32 v[14:15], v[80:81], s[2:3], v[18:19] op_sel_hi:[1,1,0]
	v_pk_fma_f32 v[16:17], v[80:81], s[18:19], v[18:19] op_sel_hi:[1,1,0]
	v_pk_fma_f32 v[18:19], v[82:83], s[44:45], v[18:19] op_sel_hi:[1,1,0]
	s_setprio 1
	s_waitcnt vmcnt(4) lgkmcnt(6)
	v_mfma_f32_32x32x16_bf16 v[2:17], v[54:57], v[98:101], v[2:17]
	v_mfma_f32_32x32x16_bf16 v[18:33], v[50:53], v[98:101], v[18:33]
	s_waitcnt vmcnt(3) lgkmcnt(5)
	v_mfma_f32_32x32x16_bf16 v[2:17], v[58:61], v[102:105], v[2:17]
	s_waitcnt lgkmcnt(4)
	v_mfma_f32_32x32x16_bf16 v[18:33], v[62:65], v[102:105], v[18:33]
	s_waitcnt vmcnt(2) lgkmcnt(3)
	v_mfma_f32_32x32x16_bf16 v[2:17], v[66:69], v[106:109], v[2:17]
	s_waitcnt lgkmcnt(2)
	v_mfma_f32_32x32x16_bf16 v[18:33], v[70:73], v[106:109], v[18:33]
	s_waitcnt vmcnt(1) lgkmcnt(1)
	v_mfma_f32_32x32x16_bf16 v[2:17], v[88:91], v[110:113], v[2:17]
	s_waitcnt lgkmcnt(0)
	v_mfma_f32_32x32x16_bf16 v[18:33], v[92:95], v[110:113], v[18:33]
	s_setprio 0
	v_cmp_lt_i32_e32 vcc, 0, v48
	s_mov_b32 s2, 0xefa18f08
	s_nop 6
	v_cndmask_b32_e32 v51, v210, v3, vcc
	v_cmp_lt_i32_e64 s[98:99], -1, v48
	v_cmp_lt_i32_e64 s[100:101], 32, v48
	v_cmp_lt_i32_e32 vcc, 31, v48
	v_cndmask_b32_e64 v55, v210, v2, s[98:99]
	v_cndmask_b32_e64 v53, v210, v19, s[100:101]
	v_cndmask_b32_e32 v58, v210, v18, vcc
	v_cmp_lt_i32_e64 s[98:99], 2, v48
	v_cmp_lt_i32_e64 s[100:101], 1, v48
	v_cmp_lt_i32_e32 vcc, 34, v48
	v_cndmask_b32_e64 v50, v210, v5, s[98:99]
	v_cndmask_b32_e64 v57, v210, v4, s[100:101]
	v_cndmask_b32_e32 v21, v210, v21, vcc
	v_cmp_lt_i32_e64 s[98:99], 33, v48
	v_cmp_lt_i32_e64 s[100:101], 4, v48
	v_cmp_lt_i32_e32 vcc, 3, v48
	v_cndmask_b32_e64 v59, v210, v20, s[98:99]
	v_cndmask_b32_e64 v18, v210, v7, s[100:101]
	v_cndmask_b32_e32 v54, v210, v6, vcc
	v_cmp_lt_i32_e64 s[98:99], 36, v48
	v_cmp_lt_i32_e64 s[100:101], 35, v48
	v_cmp_lt_i32_e32 vcc, 6, v48
	v_cndmask_b32_e64 v20, v210, v23, s[98:99]
	v_cndmask_b32_e64 v56, v210, v22, s[100:101]
	v_cndmask_b32_e32 v9, v210, v9, vcc
	v_cmp_lt_i32_e64 s[98:99], 5, v48
	v_cmp_lt_i32_e64 s[100:101], 38, v48
	v_cmp_lt_i32_e32 vcc, 37, v48
	v_cndmask_b32_e64 v52, v210, v8, s[98:99]
	v_cndmask_b32_e64 v19, v210, v25, s[100:101]
	v_cndmask_b32_e32 v25, v210, v24, vcc
	v_cmp_lt_i32_e64 s[98:99], 16, v48
	v_cmp_lt_i32_e64 s[100:101], 15, v48
	v_cmp_lt_i32_e32 vcc, 48, v48
	v_cndmask_b32_e64 v6, v210, v11, s[98:99]
	v_cndmask_b32_e64 v22, v210, v10, s[100:101]
	v_cndmask_b32_e32 v8, v210, v27, vcc
	v_cmp_lt_i32_e32 vcc, 47, v48
	s_nop 1
	v_cndmask_b32_e32 v24, v210, v26, vcc
	v_cmp_lt_i32_e32 vcc, 18, v48
	v_and_b32_e32 v26, 64, v209
	v_add_u32_e32 v26, 64, v26
	v_cndmask_b32_e32 v4, v210, v13, vcc
	v_cmp_lt_i32_e64 s[98:99], 17, v48
	v_cmp_lt_i32_e64 s[100:101], 50, v48
	v_cmp_lt_i32_e32 vcc, 49, v48
	v_cndmask_b32_e64 v13, v210, v12, s[98:99]
	v_cndmask_b32_e64 v7, v210, v29, s[100:101]
	v_cndmask_b32_e32 v23, v210, v28, vcc
	v_cmp_lt_i32_e64 s[98:99], 20, v48
	v_cmp_lt_i32_e64 s[100:101], 19, v48
	v_cmp_lt_i32_e32 vcc, 52, v48
	v_cndmask_b32_e64 v3, v210, v15, s[98:99]
	v_cndmask_b32_e64 v11, v210, v14, s[100:101]
	v_cndmask_b32_e32 v5, v210, v31, vcc
	v_cmp_lt_i32_e64 s[98:99], 51, v48
	v_cmp_lt_i32_e64 s[100:101], 22, v48
	v_cmp_lt_i32_e32 vcc, 21, v48
	v_cndmask_b32_e64 v14, v210, v30, s[98:99]
	v_cndmask_b32_e64 v2, v210, v17, s[100:101]
	v_cndmask_b32_e32 v10, v210, v16, vcc
	v_cmp_lt_i32_e32 vcc, 54, v48
	v_max_f32_e32 v16, v2, v2
	s_nop 0
	v_cndmask_b32_e32 v17, v210, v33, vcc
	v_max_f32_e32 v15, v17, v17
	v_min_f32_e32 v15, v16, v15
	v_max3_f32 v16, v15, v55, v58
	v_max3_f32 v15, v15, v51, v53
	v_cmp_lt_i32_e32 vcc, 53, v48
	v_max3_f32 v16, v16, v57, v59
	v_max3_f32 v15, v15, v50, v21
	v_max3_f32 v16, v16, v54, v56
	v_max3_f32 v15, v15, v18, v20
	s_nop 0
	v_cndmask_b32_e32 v12, v210, v32, vcc
	v_max3_f32 v16, v16, v52, v25
	v_max3_f32 v15, v15, v9, v19
	v_max3_f32 v16, v16, v22, v24
	v_max3_f32 v15, v15, v6, v8
	v_max3_f32 v16, v16, v13, v23
	v_max3_f32 v15, v15, v4, v7
	v_max3_f32 v16, v16, v11, v14
	v_max3_f32 v15, v15, v3, v5
	v_max3_f32 v16, v16, v10, v12
	v_max3_f32 v15, v15, v2, v17
	v_max_f32_e32 v15, v15, v15
	v_max_f32_e32 v16, v16, v16
	v_max_f32_e32 v15, v16, v15
	v_mov_b32_e32 v16, v15
	s_nop 1
	v_permlane32_swap_b32_e32 v16, v15
	s_waitcnt lgkmcnt(0)
	v_max_f32_e32 v15, v15, v16
	v_cmp_lt_f32_e64 s[24:25], s2, v15
	s_mov_b32 s2, 0x41000000
	v_cmp_lt_f32_e32 vcc, s2, v15
	s_mov_b32 s2, 0xc1000000
	v_cmp_gt_f32_e64 s[2:3], s2, v15
	s_and_b64 s[2:3], s[2:3], s[24:25]
	s_andn2_b64 s[2:3], s[2:3], s[0:1]
	s_or_b64 s[2:3], s[2:3], vcc
	s_and_b64 vcc, exec, s[2:3]
	s_cbranch_vccnz .LBB0_541

; template <int MODE>
; DI void bias_init(f32x16& s0, f32x16& s1, const TP& tp, float fbm, int hi) {
; #pragma unroll
;     for (int r = 0; r < 16; ++r) {
;         const int kvc = 16 * (r >> 3) + (r & 7);
;         if (MODE == 0) { s0[r] = __builtin_fmaf(-L2E, tp.cs[kvc + 8 * hi], fbm); s1[r] = __builtin_fmaf(-L2E, tp.cs[kvc + 32 + 8 * hi], fbm); }
;         else { s0[r] = __builtin_fmaf(tp.sl, (float)kvc, fbm); s1[r] = __builtin_fmaf(tp.sl, (float)(kvc + 32), fbm); }
;     }
; }
; DI float max3_asm(float a, float b, float c) { float r; asm("v_max3_f32 %0, %1, %2, %3" : "=v"(r) : "v"(a), "v"(b), "v"(c)); return r; }
; template <bool MASK>
; DI float mask_rowmax(f32x16& s0, f32x16& s1, const TP& tp) {
;     if (MASK) {
; #pragma unroll
;         for (int r = 0; r < 16; ++r) {
;             const int kvc = 16 * (r >> 3) + (r & 7);
;             const bool v0 = tp.sel && (kvc <= tp.lim) && (kvc > tp.lim2), v1 = tp.sel && (kvc + 32 <= tp.lim) && (kvc + 32 > tp.lim2);
;             s0[r] = v0 ? s0[r] : -1e30f; s1[r] = v1 ? s1[r] : -1e30f;
;         }
;     }
;     const float seed = __builtin_fminf(s0[15], s1[15]);
;     float ma = seed, mb = seed;
; #pragma unroll
;     for (int r = 0; r < 16; r += 2) { ma = max3_asm(ma, s0[r], s1[r]); mb = max3_asm(mb, s0[r + 1], s1[r + 1]); }
;     const float mx = fmaxf(ma, mb);
;     return fmaxf(mx, __shfl_xor(mx, 32));
; }
; template <int MODE, bool MASK, bool WITH_O>
; DI void attn_tile_t(lptr Kt, lptr Vt, const bf16x8 (&qf)[4], f32x16& o0, f32x16& o1, RowState& rs, const TP& tp, int lane) {
;     const int hi = lane >> 5;
;     f32x16 s0, s1;
;     bias_init<MODE>(s0, s1, tp, tp.fb - rs.mref, hi);
;     qk_acc(Kt, qf, s0, s1, lane);
;     const float mx = mask_rowmax<MASK>(s0, s1, tp);
;     const bool was = rs.seen; rs.seen = was || (mx > -1e29f);
; DI void cmpwin_unit(const Params& P, lptr L, int u, int tid, int lane, int wid) {
;     ...
;         ATT_LOOP_BEGIN(NTW, false, kb_ + (size_t)((jw0 + jt) * 64) * PROJ_LD, vb_ + (size_t)(jw0 + jt) * 64, (const float*)nullptr)
;             const int kv0 = (jw0 + jt) * 64;
;             TP tp; tp.cs = nullptr; tp.sl = sl; tp.fb = sl * (float)(kv0 + 8 * hi - t); tp.lim = t - kv0 - 8 * hi; tp.lim2 = tp.lim - 512; tp.sel = true;
;             const bool full = (kv0 + 63 <= tq0) && (tq0 + 31 - kv0 < 512);
;             attn_tile<1>(Kt, Vt, qf, o0, o1, rs, tp, !full, lane);
.LBB0_581:
	s_and_b32 s54, s53, 1
	s_mul_i32 s2, s54, 0x2400
	v_add_u32_e32 v34, s43, v161
	s_add_i32 s55, s2, 0
	s_add_i32 s2, s43, 63
	v_cvt_f32_i32_e32 v34, v34
	s_cmp_gt_u32 s2, s81
	s_cselect_b64 s[2:3], -1, 0
	s_cmp_lt_i32 s43, s23
	s_cselect_b64 s[28:29], -1, 0
	s_or_b64 s[2:3], s[2:3], s[28:29]
	v_mul_f32_e32 v216, v150, v34
	s_andn2_b64 vcc, exec, s[2:3]
	s_mov_b64 s[2:3], -1
	s_cbranch_vccz .LBB0_590
	v_add3_u32 v234, s55, v131, v133
	ds_read_b128 v[34:37], v234 offset:4608
	ds_read_b128 v[38:41], v234
	ds_read_b128 v[42:45], v234 offset:32
	ds_read_b128 v[46:49], v234 offset:4640
	ds_read_b128 v[50:53], v234 offset:64
	ds_read_b128 v[54:57], v234 offset:4672
	ds_read_b128 v[58:61], v234 offset:96
	ds_read_b128 v[62:65], v234 offset:4704
	s_mov_b32 s2, 2.0
	v_sub_f32_e32 v232, v216, v215
	s_mov_b32 s3, 0x40400000
	v_pk_fma_f32 v[84:85], v[166:167], s[2:3], v[232:233] op_sel_hi:[1,1,0]
	s_mov_b32 s2, 4.0
	s_mov_b32 s3, 0x40a00000
	v_pk_fma_f32 v[86:87], v[166:167], s[2:3], v[232:233] op_sel_hi:[1,1,0]
	s_mov_b32 s2, 0x40c00000
	s_mov_b32 s3, 0x40e00000
	v_pk_fma_f32 v[88:89], v[166:167], s[2:3], v[232:233] op_sel_hi:[1,1,0]
	s_mov_b32 s2, 0x41800000
	s_mov_b32 s3, 0x41880000
	v_pk_fma_f32 v[90:91], v[166:167], s[2:3], v[232:233] op_sel_hi:[1,1,0]
	s_mov_b32 s2, 0x41900000
	s_mov_b32 s3, 0x41980000
	v_pk_fma_f32 v[92:93], v[166:167], s[2:3], v[232:233] op_sel_hi:[1,1,0]
	s_mov_b32 s2, 0x41a00000
	s_mov_b32 s3, 0x41a80000
	v_mov_b32_e32 v151, v150
	v_fma_f32 v82, 0, v150, v232
	v_add_f32_e32 v83, v150, v232
	v_pk_fma_f32 v[94:95], v[166:167], s[2:3], v[232:233] op_sel_hi:[1,1,0]
	v_pk_fma_f32 v[96:97], v[166:167], s[18:19], v[232:233] op_sel_hi:[1,1,0]
	v_pk_fma_f32 v[80:81], v[150:151], s[4:5], v[232:233] op_sel_hi:[1,1,0]
	v_pk_fma_f32 v[78:79], v[150:151], s[14:15], v[232:233] op_sel_hi:[1,1,0]
	v_pk_fma_f32 v[76:77], v[150:151], s[16:17], v[232:233] op_sel_hi:[1,1,0]
	v_pk_fma_f32 v[74:75], v[150:151], s[94:95], v[232:233] op_sel_hi:[1,1,0]
	v_pk_fma_f32 v[72:73], v[150:151], s[96:97], v[232:233] op_sel_hi:[1,1,0]
	v_pk_fma_f32 v[70:71], v[150:151], s[84:85], v[232:233] op_sel_hi:[1,1,0]
	v_pk_fma_f32 v[68:69], v[150:151], s[72:73], v[232:233] op_sel_hi:[1,1,0]
	v_pk_fma_f32 v[66:67], v[168:169], s[44:45], v[232:233] op_sel_hi:[1,1,0]
	s_setprio 1
	s_waitcnt lgkmcnt(6)
	v_mfma_f32_32x32x16_bf16 v[82:97], v[38:41], v[98:101], v[82:97]
	v_mfma_f32_32x32x16_bf16 v[66:81], v[34:37], v[98:101], v[66:81]
	s_waitcnt lgkmcnt(5)
	v_mfma_f32_32x32x16_bf16 v[82:97], v[42:45], v[102:105], v[82:97]
	s_waitcnt lgkmcnt(4)
	v_mfma_f32_32x32x16_bf16 v[66:81], v[46:49], v[102:105], v[66:81]
	s_waitcnt lgkmcnt(3)
	v_mfma_f32_32x32x16_bf16 v[82:97], v[50:53], v[106:109], v[82:97]
	s_waitcnt lgkmcnt(2)
	v_mfma_f32_32x32x16_bf16 v[66:81], v[54:57], v[106:109], v[66:81]
	s_waitcnt lgkmcnt(1)
	v_mfma_f32_32x32x16_bf16 v[82:97], v[58:61], v[110:113], v[82:97]
	s_waitcnt lgkmcnt(0)
	v_mfma_f32_32x32x16_bf16 v[66:81], v[62:65], v[110:113], v[66:81]
	s_setprio 0
	s_nop 10
	v_max_f32_e32 v34, v81, v81
	v_max_f32_e32 v35, v97, v97
	v_min_f32_e32 v34, v35, v34
	v_max3_f32 v35, v34, v82, v66
	v_max3_f32 v34, v34, v83, v67
	s_mov_b32 s2, 0xefa18f08
	v_max3_f32 v35, v35, v84, v68
	v_max3_f32 v34, v34, v85, v69
	s_mov_b64 s[30:31], -1
	v_max3_f32 v35, v35, v86, v70
	v_max3_f32 v34, v34, v87, v71
	v_max3_f32 v35, v35, v88, v72
	v_max3_f32 v34, v34, v89, v73
	v_max3_f32 v35, v35, v90, v74
	v_max3_f32 v34, v34, v91, v75
	v_max3_f32 v35, v35, v92, v76
	v_max3_f32 v34, v34, v93, v77
	v_max3_f32 v35, v35, v94, v78
	v_max3_f32 v34, v34, v95, v79
	v_max3_f32 v35, v35, v96, v80
	v_max3_f32 v34, v34, v97, v81
	v_max_f32_e32 v34, v34, v34
	v_max_f32_e32 v35, v35, v35
	v_max_f32_e32 v34, v35, v34
	v_mov_b32_e32 v35, v34
	s_nop 1
	v_permlane32_swap_b32_e32 v35, v34
	s_waitcnt lgkmcnt(0)
	v_max_f32_e32 v218, v34, v35
	v_cmp_lt_f32_e64 s[28:29], s2, v218
	s_mov_b32 s2, 0x41000000
	v_cmp_lt_f32_e32 vcc, s2, v218
	s_mov_b32 s30, 0xc1000000
	v_cmp_gt_f32_e64 s[30:31], s30, v218
	s_and_b64 s[30:31], s[30:31], s[28:29]
	s_andn2_b64 s[30:31], s[30:31], s[24:25]
	s_or_b64 s[30:31], s[30:31], vcc
	s_and_b64 vcc, exec, s[30:31]
	v_mov_b32_e32 v217, v163
	v_mov_b32_e32 v151, v215
	s_cbranch_vccnz .LBB0_595

; #define LAS __attribute__((address_space(3)))
; #define MFMA32(a, b, c) __builtin_amdgcn_mfma_f32_32x32x16_bf16((a), (b), (c), 0, 0, 0)
; DI void qk_acc(lptr Kt, const bf16x8 (&qf)[4], f32x16& s0, f32x16& s1, int lane) {
;     const int i = lane & 31, hi = lane >> 5;
;     const int krow = (i & 19) | ((i & 4) << 1) | ((i & 8) >> 1);
;     lptr kp = Kt + krow * KPB + hi * 16;
;     bf16x8 a0[4], a1[4];
; #pragma unroll
;     for (int d0 = 0; d0 < 4; ++d0) { a0[d0] = *(LAS bf16x8*)(kp + d0 * 32); a1[d0] = *(LAS bf16x8*)(kp + 32 * KPB + d0 * 32); }
;     __builtin_amdgcn_s_setprio(1);
; #pragma unroll
;     for (int d0 = 0; d0 < 4; ++d0) { s0 = MFMA32(a0[d0], qf[d0], s0); s1 = MFMA32(a1[d0], qf[d0], s1); }
;     __builtin_amdgcn_s_setprio(0);
; template <int MODE>
; DI void bias_init(f32x16& s0, f32x16& s1, const TP& tp, float fbm, int hi) {
; #pragma unroll
;     for (int r = 0; r < 16; ++r) {
;         const int kvc = 16 * (r >> 3) + (r & 7);
;         if (MODE == 0) { s0[r] = __builtin_fmaf(-L2E, tp.cs[kvc + 8 * hi], fbm); s1[r] = __builtin_fmaf(-L2E, tp.cs[kvc + 32 + 8 * hi], fbm); }
;         else { s0[r] = __builtin_fmaf(tp.sl, (float)kvc, fbm); s1[r] = __builtin_fmaf(tp.sl, (float)(kvc + 32), fbm); }
.LBB0_590:
	s_and_b64 vcc, exec, s[2:3]
	s_cbranch_vccz .LBB0_586
	s_mov_b32 s2, 2.0
	v_sub_f32_e32 v50, v216, v215
	s_mov_b32 s3, 0x40400000
	v_add3_u32 v94, s55, v131, v133
	v_pk_fma_f32 v[36:37], v[166:167], s[2:3], v[50:51] op_sel_hi:[1,1,0]
	s_mov_b32 s2, 4.0
	ds_read_b128 v[66:69], v94 offset:4608
	ds_read_b128 v[70:73], v94
	ds_read_b128 v[74:77], v94 offset:32
	ds_read_b128 v[78:81], v94 offset:4640
	ds_read_b128 v[82:85], v94 offset:64
	ds_read_b128 v[86:89], v94 offset:4672
	ds_read_b128 v[90:93], v94 offset:96
	ds_read_b128 v[94:97], v94 offset:4704
	s_mov_b32 s3, 0x40a00000
	v_pk_fma_f32 v[38:39], v[166:167], s[2:3], v[50:51] op_sel_hi:[1,1,0]
	s_mov_b32 s2, 0x40c00000
	s_mov_b32 s3, 0x40e00000
	v_pk_fma_f32 v[40:41], v[166:167], s[2:3], v[50:51] op_sel_hi:[1,1,0]
	s_mov_b32 s2, 0x41800000
	s_mov_b32 s3, 0x41880000
	v_pk_fma_f32 v[42:43], v[166:167], s[2:3], v[50:51] op_sel_hi:[1,1,0]
	s_mov_b32 s2, 0x41900000
	s_mov_b32 s3, 0x41980000
	v_pk_fma_f32 v[44:45], v[166:167], s[2:3], v[50:51] op_sel_hi:[1,1,0]
	s_mov_b32 s2, 0x41a00000
	s_mov_b32 s3, 0x41a80000
	v_mov_b32_e32 v151, v150
	v_fma_f32 v34, 0, v150, v50
	v_add_f32_e32 v35, v150, v50
	v_pk_fma_f32 v[46:47], v[166:167], s[2:3], v[50:51] op_sel_hi:[1,1,0]
	v_pk_fma_f32 v[48:49], v[166:167], s[18:19], v[50:51] op_sel_hi:[1,1,0]
	v_pk_fma_f32 v[64:65], v[150:151], s[4:5], v[50:51] op_sel_hi:[1,1,0]
	v_pk_fma_f32 v[62:63], v[150:151], s[14:15], v[50:51] op_sel_hi:[1,1,0]
	v_pk_fma_f32 v[60:61], v[150:151], s[16:17], v[50:51] op_sel_hi:[1,1,0]
	v_pk_fma_f32 v[58:59], v[150:151], s[94:95], v[50:51] op_sel_hi:[1,1,0]
	v_pk_fma_f32 v[56:57], v[150:151], s[96:97], v[50:51] op_sel_hi:[1,1,0]
	v_pk_fma_f32 v[54:55], v[150:151], s[84:85], v[50:51] op_sel_hi:[1,1,0]
	v_pk_fma_f32 v[52:53], v[150:151], s[72:73], v[50:51] op_sel_hi:[1,1,0]
	v_pk_fma_f32 v[50:51], v[168:169], s[44:45], v[50:51] op_sel_hi:[1,1,0]
	s_setprio 1
	s_waitcnt lgkmcnt(6)
	v_mfma_f32_32x32x16_bf16 v[34:49], v[70:73], v[98:101], v[34:49]
	v_mfma_f32_32x32x16_bf16 v[50:65], v[66:69], v[98:101], v[50:65]
	s_waitcnt lgkmcnt(5)
	v_mfma_f32_32x32x16_bf16 v[34:49], v[74:77], v[102:105], v[34:49]
	s_waitcnt lgkmcnt(4)
	v_mfma_f32_32x32x16_bf16 v[50:65], v[78:81], v[102:105], v[50:65]
	s_waitcnt lgkmcnt(3)
	v_mfma_f32_32x32x16_bf16 v[34:49], v[82:85], v[106:109], v[34:49]
	s_waitcnt lgkmcnt(2)
	v_mfma_f32_32x32x16_bf16 v[50:65], v[86:89], v[106:109], v[50:65]
	s_waitcnt lgkmcnt(1)
	v_mfma_f32_32x32x16_bf16 v[34:49], v[90:93], v[110:113], v[34:49]
	s_waitcnt lgkmcnt(0)
; DI float max3_asm(float a, float b, float c) { float r; asm("v_max3_f32 %0, %1, %2, %3" : "=v"(r) : "v"(a), "v"(b), "v"(c)); return r; }
; template <bool MASK>
; DI float mask_rowmax(f32x16& s0, f32x16& s1, const TP& tp) {
;     ...
;         for (int r = 0; r < 16; ++r) {
;             const int kvc = 16 * (r >> 3) + (r & 7);
;             const bool v0 = tp.sel && (kvc <= tp.lim) && (kvc > tp.lim2), v1 = tp.sel && (kvc + 32 <= tp.lim) && (kvc + 32 > tp.lim2);
;             s0[r] = v0 ? s0[r] : -1e30f; s1[r] = v1 ? s1[r] : -1e30f;
;         }
;     }
;     const float seed = __builtin_fminf(s0[15], s1[15]);
;     float ma = seed, mb = seed;
; #pragma unroll
;     for (int r = 0; r < 16; r += 2) { ma = max3_asm(ma, s0[r], s1[r]); mb = max3_asm(mb, s0[r + 1], s1[r + 1]); }
;     const float mx = fmaxf(ma, mb);
;     return fmaxf(mx, __shfl_xor(mx, 32));
; }
; template <int MODE, bool MASK, bool WITH_O>
; DI void attn_tile_t(lptr Kt, lptr Vt, const bf16x8 (&qf)[4], f32x16& o0, f32x16& o1, RowState& rs, const TP& tp, int lane) {
;     const int hi = lane >> 5;
;     f32x16 s0, s1;
;     bias_init<MODE>(s0, s1, tp, tp.fb - rs.mref, hi);
;     qk_acc(Kt, qf, s0, s1, lane);
;     const float mx = mask_rowmax<MASK>(s0, s1, tp);
;     const bool was = rs.seen; rs.seen = was || (mx > -1e29f);
;     const bool trig = (mx > 8.f) || (!was && mx > -1e29f && mx < -8.f);
	v_mfma_f32_32x32x16_bf16 v[50:65], v[94:97], v[110:113], v[50:65]
	s_setprio 0
	v_add_u32_e32 v66, -1, v155
	v_cmp_gt_u32_e32 vcc, s10, v66
	s_mov_b32 s2, 0xefa18f08
	s_nop 5
	v_cndmask_b32_e32 v68, v210, v35, vcc
	v_cmp_gt_u32_e32 vcc, s10, v155
	v_subrev_u32_e32 v35, 32, v155
	s_nop 0
	v_cndmask_b32_e32 v75, v210, v34, vcc
	v_subrev_u32_e32 v34, 33, v155
	v_cmp_gt_u32_e32 vcc, s10, v34
	v_add_u32_e32 v34, -3, v155
	s_nop 0
	v_cndmask_b32_e32 v51, v210, v51, vcc
	v_cmp_gt_u32_e32 vcc, s10, v35
	v_add_u32_e32 v35, -2, v155
	s_nop 0
	v_cndmask_b32_e32 v67, v210, v50, vcc
	v_cmp_gt_u32_e32 vcc, s10, v34
	v_subrev_u32_e32 v34, 35, v155
	s_nop 0
	v_cndmask_b32_e32 v69, v210, v37, vcc
	v_cmp_gt_u32_e32 vcc, s10, v35
	v_subrev_u32_e32 v35, 34, v155
	v_subrev_u32_e32 v37, 20, v155
	v_cndmask_b32_e32 v72, v210, v36, vcc
	v_cmp_gt_u32_e32 vcc, s10, v34
	v_add_u32_e32 v34, -5, v155
	v_subrev_u32_e32 v36, 48, v155
	v_cndmask_b32_e32 v50, v210, v53, vcc
	v_cmp_gt_u32_e32 vcc, s10, v35
	v_add_u32_e32 v35, -4, v155
	s_nop 0
	v_cndmask_b32_e32 v66, v210, v52, vcc
	v_cmp_gt_u32_e32 vcc, s10, v34
	v_subrev_u32_e32 v34, 37, v155
	s_nop 0
	v_cndmask_b32_e32 v70, v210, v39, vcc
	v_cmp_gt_u32_e32 vcc, s10, v35
	v_subrev_u32_e32 v35, 36, v155
	s_nop 0
	v_cndmask_b32_e32 v73, v210, v38, vcc
	v_cmp_gt_u32_e32 vcc, s10, v34
	v_add_u32_e32 v34, -7, v155
	s_nop 0
	v_cndmask_b32_e32 v52, v210, v55, vcc
	v_cmp_gt_u32_e32 vcc, s10, v35
	v_add_u32_e32 v35, -6, v155
	s_nop 0
	v_cndmask_b32_e32 v54, v210, v54, vcc
	v_cmp_gt_u32_e32 vcc, s10, v34
	v_subrev_u32_e32 v34, 39, v155
	s_nop 0
	v_cndmask_b32_e32 v71, v210, v41, vcc
	v_cmp_gt_u32_e32 vcc, s10, v35
	v_subrev_u32_e32 v35, 38, v155
	s_nop 0
	v_cndmask_b32_e32 v74, v210, v40, vcc
	v_cmp_gt_u32_e32 vcc, s10, v34
	v_add_u32_e32 v34, -16, v155
	v_subrev_u32_e32 v40, 22, v155
	v_cndmask_b32_e32 v53, v210, v57, vcc
	v_cmp_gt_u32_e32 vcc, s10, v35
	v_subrev_u32_e32 v35, 17, v155
	s_nop 0
	v_cndmask_b32_e32 v55, v210, v56, vcc
	v_cmp_gt_u32_e32 vcc, s10, v35
	s_nop 1
	v_cndmask_b32_e32 v43, v210, v43, vcc
	v_cmp_gt_u32_e32 vcc, s10, v34
	v_subrev_u32_e32 v34, 49, v155
	s_nop 0
	v_cndmask_b32_e32 v57, v210, v42, vcc
	v_cmp_gt_u32_e32 vcc, s10, v34
	v_subrev_u32_e32 v34, 19, v155
	s_nop 0
	v_cndmask_b32_e32 v35, v210, v59, vcc
	v_cmp_gt_u32_e32 vcc, s10, v36
	v_subrev_u32_e32 v36, 18, v155
	s_nop 0
	v_cndmask_b32_e32 v41, v210, v58, vcc
	v_cmp_gt_u32_e32 vcc, s10, v34
	v_subrev_u32_e32 v34, 51, v155
	s_nop 0
	v_cndmask_b32_e32 v42, v210, v45, vcc
	v_cmp_gt_u32_e32 vcc, s10, v36
	v_subrev_u32_e32 v36, 50, v155
	s_nop 0
	v_cndmask_b32_e32 v56, v210, v44, vcc
	v_cmp_gt_u32_e32 vcc, s10, v34
	s_nop 1
	v_cndmask_b32_e32 v34, v210, v61, vcc
	v_cmp_gt_u32_e32 vcc, s10, v36
	v_subrev_u32_e32 v36, 21, v155
	s_nop 0
	v_cndmask_b32_e32 v38, v210, v60, vcc
	v_cmp_gt_u32_e32 vcc, s10, v36
	v_subrev_u32_e32 v36, 53, v155
	s_nop 0
	v_cndmask_b32_e32 v44, v210, v47, vcc
	v_cmp_gt_u32_e32 vcc, s10, v37
	v_subrev_u32_e32 v37, 52, v155
	s_nop 0
	v_cndmask_b32_e32 v46, v210, v46, vcc
	v_cmp_gt_u32_e32 vcc, s10, v36
	s_nop 1
	v_cndmask_b32_e32 v36, v210, v63, vcc
	v_cmp_gt_u32_e32 vcc, s10, v37
	v_subrev_u32_e32 v37, 23, v155
	s_nop 0
	v_cndmask_b32_e32 v39, v210, v62, vcc
	v_cmp_gt_u32_e32 vcc, s10, v37
	v_subrev_u32_e32 v37, 55, v155
	s_nop 0
	v_cndmask_b32_e32 v45, v210, v49, vcc
	v_cmp_gt_u32_e32 vcc, s10, v40
	v_max_f32_e32 v49, v45, v45
	v_subrev_u32_e32 v40, 54, v155
	v_cndmask_b32_e32 v47, v210, v48, vcc
	v_cmp_gt_u32_e32 vcc, s10, v37
	s_nop 1
	v_cndmask_b32_e32 v37, v210, v65, vcc
	v_max_f32_e32 v48, v37, v37
	v_min_f32_e32 v48, v49, v48
	v_max3_f32 v49, v48, v75, v67
	v_max3_f32 v48, v48, v68, v51
	v_cmp_gt_u32_e32 vcc, s10, v40
	v_max3_f32 v49, v49, v72, v66
	v_max3_f32 v48, v48, v69, v50
	v_max3_f32 v49, v49, v73, v54
	v_max3_f32 v48, v48, v70, v52
	s_nop 0
	v_cndmask_b32_e32 v40, v210, v64, vcc
	v_max3_f32 v49, v49, v74, v55
	v_max3_f32 v48, v48, v71, v53
	v_max3_f32 v49, v49, v57, v41
	v_max3_f32 v48, v48, v43, v35
	v_max3_f32 v49, v49, v56, v38
	v_max3_f32 v48, v48, v42, v34
	v_max3_f32 v49, v49, v46, v39
	v_max3_f32 v48, v48, v44, v36
	v_max3_f32 v49, v49, v47, v40
	v_max3_f32 v48, v48, v45, v37
	v_max_f32_e32 v48, v48, v48
	v_max_f32_e32 v49, v49, v49
	v_max_f32_e32 v48, v49, v48
	v_mov_b32_e32 v49, v48
	s_nop 1
	v_permlane32_swap_b32_e32 v49, v48
	s_waitcnt lgkmcnt(0)
	v_max_f32_e32 v48, v48, v49
	v_cmp_lt_f32_e64 s[28:29], s2, v48
	s_mov_b32 s2, 0x41000000
	v_cmp_lt_f32_e32 vcc, s2, v48
	s_mov_b32 s2, 0xc1000000
	v_cmp_gt_f32_e64 s[2:3], s2, v48
	s_and_b64 s[2:3], s[2:3], s[28:29]
	s_andn2_b64 s[2:3], s[2:3], s[24:25]
	s_or_b64 s[2:3], s[2:3], vcc
	s_and_b64 vcc, exec, s[2:3]
	s_cbranch_vccnz .LBB0_596

; template <int MODE>
; DI void bias_init(f32x16& s0, f32x16& s1, const TP& tp, float fbm, int hi) {
; #pragma unroll
;     for (int r = 0; r < 16; ++r) {
;         const int kvc = 16 * (r >> 3) + (r & 7);
;         if (MODE == 0) { s0[r] = __builtin_fmaf(-L2E, tp.cs[kvc + 8 * hi], fbm); s1[r] = __builtin_fmaf(-L2E, tp.cs[kvc + 32 + 8 * hi], fbm); }
;         else { s0[r] = __builtin_fmaf(tp.sl, (float)kvc, fbm); s1[r] = __builtin_fmaf(tp.sl, (float)(kvc + 32), fbm); }
;     }
; }
; DI float max3_asm(float a, float b, float c) { float r; asm("v_max3_f32 %0, %1, %2, %3" : "=v"(r) : "v"(a), "v"(b), "v"(c)); return r; }
; template <bool MASK>
; DI float mask_rowmax(f32x16& s0, f32x16& s1, const TP& tp) {
;     if (MASK) {
; #pragma unroll
;         for (int r = 0; r < 16; ++r) {
;             const int kvc = 16 * (r >> 3) + (r & 7);
;             const bool v0 = tp.sel && (kvc <= tp.lim) && (kvc > tp.lim2), v1 = tp.sel && (kvc + 32 <= tp.lim) && (kvc + 32 > tp.lim2);
;             s0[r] = v0 ? s0[r] : -1e30f; s1[r] = v1 ? s1[r] : -1e30f;
;         }
;     }
;     const float seed = __builtin_fminf(s0[15], s1[15]);
;     float ma = seed, mb = seed;
; #pragma unroll
;     for (int r = 0; r < 16; r += 2) { ma = max3_asm(ma, s0[r], s1[r]); mb = max3_asm(mb, s0[r + 1], s1[r + 1]); }
;     const float mx = fmaxf(ma, mb);
;     return fmaxf(mx, __shfl_xor(mx, 32));
; }
; template <int MODE, bool MASK, bool WITH_O>
; DI void attn_tile_t(lptr Kt, lptr Vt, const bf16x8 (&qf)[4], f32x16& o0, f32x16& o1, RowState& rs, const TP& tp, int lane) {
;     const int hi = lane >> 5;
;     f32x16 s0, s1;
;     bias_init<MODE>(s0, s1, tp, tp.fb - rs.mref, hi);
;     qk_acc(Kt, qf, s0, s1, lane);
;     const float mx = mask_rowmax<MASK>(s0, s1, tp);
; DI void slc_unit(const Params& P, lptr L, int u, int tid, int lane, int wid) {
;     ...
;     ATT_LOOP_BEGIN(NTS, false, kb_ + (size_t)((int)list[jt] * 64) * PROJ_LD, vb_ + (size_t)((int)list[jt]) * 64, (const float*)nullptr)
;         const int j = (int)list[jt], kv0 = j * 64;
;         const bool sel = (sm[ql * 8 + (j >> 5)] >> (j & 31)) & 1u;
;         if (__any(sel)) {
;             TP tp; tp.cs = nullptr; tp.sl = sl; tp.fb = sl * (float)(kv0 + 8 * hi - t); tp.lim = t - kv0 - 8 * hi; tp.lim2 = -(1 << 30); tp.sel = sel;
;             attn_tile<1>(Kt, Vt, qf, o0, o1, rs, tp, true, lane);
;         }
.LBB0_613:
	v_mov_b32_e32 v0, v253
	s_and_b32 s31, s0, 1
	v_and_b32_e32 v35, 31, v253
	s_waitcnt lgkmcnt(0)
	v_lshrrev_b32_e32 v36, v0, v255
	v_bfe_u32 v34, v255, v35, 1
	v_and_b32_e32 v35, 1, v36
	v_mov_b32_e32 v253, v254
	v_cmp_ne_u32_e32 vcc, 0, v34
	v_cmp_eq_u32_e64 s[28:29], 1, v35
	s_cbranch_vccz .LBB0_618
	s_mul_i32 s33, s31, 0x2400
	v_add_u32_e32 v232, s33, v170
	ds_read_b128 v[102:105], v232 offset:4608
	ds_read_b128 v[106:109], v232
	ds_read_b128 v[110:113], v232 offset:32
	ds_read_b128 v[114:117], v232 offset:4640
	ds_read_b128 v[118:121], v232 offset:64
	ds_read_b128 v[158:161], v232 offset:4672
	ds_read_b128 v[162:165], v232 offset:96
	ds_read_b128 v[166:169], v232 offset:4704
	v_lshl_or_b32 v0, v0, 6, v126
	v_sub_u32_e32 v34, v0, v91
	v_cvt_f32_i32_e32 v34, v34
	s_mov_b32 s0, 2.0
	v_sub_u32_e32 v152, v91, v0
	s_mov_b32 s1, 0x40400000
	v_cmp_lt_i32_e32 vcc, 54, v152
	v_fma_f32 v0, v150, v34, -v101
	s_cmp_eq_u64 vcc, exec
	s_cselect_b64 s[98:99], -1, 0
	s_orn2_b64 s[100:101], s[28:29], s[98:99]
	v_cndmask_b32_e64 v0, v210, v0, s[100:101]
	v_pk_fma_f32 v[36:37], v[94:95], s[0:1], v[0:1] op_sel_hi:[1,1,0]
	s_mov_b32 s0, 4.0
	s_mov_b32 s1, 0x40a00000
	v_pk_fma_f32 v[38:39], v[94:95], s[0:1], v[0:1] op_sel_hi:[1,1,0]
	s_mov_b32 s0, 0x40c00000
	s_mov_b32 s1, 0x40e00000
	v_pk_fma_f32 v[40:41], v[94:95], s[0:1], v[0:1] op_sel_hi:[1,1,0]
	s_mov_b32 s0, 0x41800000
	s_mov_b32 s1, 0x41880000
	v_pk_fma_f32 v[42:43], v[94:95], s[0:1], v[0:1] op_sel_hi:[1,1,0]
	s_mov_b32 s0, 0x41900000
	s_mov_b32 s1, 0x41980000
	v_pk_fma_f32 v[44:45], v[94:95], s[0:1], v[0:1] op_sel_hi:[1,1,0]
	s_mov_b32 s0, 0x41a00000
	s_mov_b32 s1, 0x41a80000
	v_mov_b32_e32 v151, v150
	v_fma_f32 v34, 0, v150, v0
	v_add_f32_e32 v35, v150, v0
	v_pk_fma_f32 v[46:47], v[94:95], s[0:1], v[0:1] op_sel_hi:[1,1,0]
	v_pk_fma_f32 v[48:49], v[94:95], s[18:19], v[0:1] op_sel_hi:[1,1,0]
	v_pk_fma_f32 v[64:65], v[150:151], s[4:5], v[0:1] op_sel_hi:[1,1,0]
	v_pk_fma_f32 v[62:63], v[150:151], s[14:15], v[0:1] op_sel_hi:[1,1,0]
	v_pk_fma_f32 v[60:61], v[150:151], s[16:17], v[0:1] op_sel_hi:[1,1,0]
	v_pk_fma_f32 v[58:59], v[150:151], s[94:95], v[0:1] op_sel_hi:[1,1,0]
	v_pk_fma_f32 v[56:57], v[150:151], s[96:97], v[0:1] op_sel_hi:[1,1,0]
	v_pk_fma_f32 v[54:55], v[150:151], s[84:85], v[0:1] op_sel_hi:[1,1,0]
	v_pk_fma_f32 v[52:53], v[150:151], s[72:73], v[0:1] op_sel_hi:[1,1,0]
	v_pk_fma_f32 v[50:51], v[96:97], s[44:45], v[0:1] op_sel_hi:[1,1,0]
	s_setprio 1
	s_waitcnt lgkmcnt(6)
	v_mfma_f32_32x32x16_bf16 v[34:49], v[106:109], v[66:69], v[34:49]
	v_mfma_f32_32x32x16_bf16 v[50:65], v[102:105], v[66:69], v[50:65]
	s_waitcnt lgkmcnt(5)
	v_mfma_f32_32x32x16_bf16 v[34:49], v[110:113], v[70:73], v[34:49]
	s_waitcnt lgkmcnt(4)
	v_mfma_f32_32x32x16_bf16 v[50:65], v[114:117], v[70:73], v[50:65]
	s_waitcnt lgkmcnt(3)
	v_mfma_f32_32x32x16_bf16 v[34:49], v[118:121], v[74:77], v[34:49]
	s_waitcnt lgkmcnt(2)
	v_mfma_f32_32x32x16_bf16 v[50:65], v[158:161], v[74:77], v[50:65]
	s_waitcnt lgkmcnt(1)
	v_mfma_f32_32x32x16_bf16 v[34:49], v[162:165], v[78:81], v[34:49]
	s_waitcnt lgkmcnt(0)
	v_mfma_f32_32x32x16_bf16 v[50:65], v[166:169], v[78:81], v[50:65]
	s_setprio 0
	s_and_b64 vcc, exec, s[98:99]
	s_cbranch_vccz .Lslc_masked
	s_nop 10
	v_max_f32_e32 v252, v65, v65
	v_max_f32_e32 v228, v49, v49
	v_min_f32_e32 v252, v228, v252
	v_max3_f32 v228, v252, v34, v50
	v_max3_f32 v252, v252, v35, v51
	s_mov_b32 s0, 0xefa18f08
	v_max3_f32 v228, v228, v36, v52
	v_max3_f32 v252, v252, v37, v53
	v_max3_f32 v228, v228, v38, v54
	v_max3_f32 v252, v252, v39, v55
	v_max3_f32 v228, v228, v40, v56
	v_max3_f32 v252, v252, v41, v57
	v_max3_f32 v228, v228, v42, v58
	v_max3_f32 v252, v252, v43, v59
	v_max3_f32 v228, v228, v44, v60
	v_max3_f32 v252, v252, v45, v61
	v_max3_f32 v228, v228, v46, v62
	v_max3_f32 v252, v252, v47, v63
	v_max3_f32 v228, v228, v48, v64
	v_max3_f32 v252, v252, v49, v65
	v_max_f32_e32 v252, v252, v252
	v_max_f32_e32 v228, v228, v228
	v_max_f32_e32 v252, v228, v252
	v_mov_b32_e32 v228, v252
	s_nop 1
	v_permlane32_swap_b32_e32 v228, v252
	s_waitcnt lgkmcnt(0)
	v_max_f32_e32 v252, v252, v228
	v_cmp_lt_f32_e64 s[28:29], s0, v252
	s_mov_b32 s0, 0x41000000
	v_cmp_lt_f32_e32 vcc, s0, v252
	s_mov_b32 s0, 0xc1000000
	v_cmp_gt_f32_e64 s[0:1], s0, v252
	s_and_b64 s[0:1], s[0:1], s[28:29]
	s_andn2_b64 s[0:1], s[0:1], s[22:23]
	s_or_b64 s[0:1], s[0:1], vcc
	s_and_b64 vcc, exec, s[0:1]
	s_cbranch_vccnz .Lsf_rare
; template <int MODE, bool MASK, bool WITH_O>
; DI void attn_tile_t(lptr Kt, lptr Vt, const bf16x8 (&qf)[4], f32x16& o0, f32x16& o1, RowState& rs, const TP& tp, int lane) {
;     ...
;         const int i = lane & 31;
;         lptr vp = Vt + i * KPB + hi * 16;
;         float sum = 0.f;
;     ...
;         PV_STEP(s0, 0, 0) PV_STEP(s0, 8, 32) PV_STEP(s1, 0, 64) PV_STEP(s1, 8, 96)
;     ...
;         rs.l += sum;
	v_exp_f32_e32 v252, v34
	v_exp_f32_e32 v103, v35
	v_exp_f32_e32 v111, v36
	v_exp_f32_e32 v105, v37
	v_add_f32_e32 v106, 0, v252
	v_add_f32_e32 v106, v103, v106
	v_add_f32_e32 v104, v111, v106
	v_exp_f32_e32 v106, v38
	v_exp_f32_e32 v107, v39
	v_add_u32_e32 v228, s33, v172
	v_exp_f32_e32 v108, v40
	ds_read_b128 v[236:239], v228 offset:18432
	ds_read_b128 v[240:243], v228 offset:23040
	v_add_f32_e32 v104, v105, v104
	v_exp_f32_e32 v109, v41
	v_add_f32_e32 v104, v106, v104
	v_add_f32_e32 v104, v107, v104
	v_add_f32_e32 v104, v108, v104
	v_add_f32_e32 v110, v109, v104
	v_cvt_pk_bf16_f32 v104, v252, v103
	v_cvt_pk_bf16_f32 v105, v111, v105
	v_cvt_pk_bf16_f32 v106, v106, v107
	v_cvt_pk_bf16_f32 v107, v108, v109
	s_or_b64 s[22:23], s[22:23], s[28:29]
	s_waitcnt lgkmcnt(1)
	v_mfma_f32_32x32x16_bf16 v[18:33], v[236:239], v[104:107], v[18:33]
	s_waitcnt lgkmcnt(0)
	v_mfma_f32_32x32x16_bf16 v[2:17], v[240:243], v[104:107], v[2:17]
	v_exp_f32_e32 v252, v42
	v_exp_f32_e32 v43, v43
	v_exp_f32_e32 v103, v44
	v_exp_f32_e32 v44, v45
	v_add_f32_e32 v229, v252, v110
	v_exp_f32_e32 v45, v46
	v_add_f32_e32 v229, v43, v229
	v_exp_f32_e32 v46, v47
	v_add_f32_e32 v42, v103, v229
	v_exp_f32_e32 v47, v48
	ds_read_b128 v[236:239], v228 offset:18464
	ds_read_b128 v[240:243], v228 offset:23072
	v_add_f32_e32 v42, v44, v42
	v_exp_f32_e32 v48, v49
	v_add_f32_e32 v42, v45, v42
	v_add_f32_e32 v42, v46, v42
	v_add_f32_e32 v42, v47, v42
	v_add_f32_e32 v229, v48, v42
	v_cvt_pk_bf16_f32 v42, v252, v43
	v_cvt_pk_bf16_f32 v43, v103, v44
	v_cvt_pk_bf16_f32 v44, v45, v46
	v_cvt_pk_bf16_f32 v45, v47, v48
	s_waitcnt lgkmcnt(1)
	s_nop 0
	v_mfma_f32_32x32x16_bf16 v[18:33], v[236:239], v[42:45], v[18:33]
	s_waitcnt lgkmcnt(0)
	v_mfma_f32_32x32x16_bf16 v[2:17], v[240:243], v[42:45], v[2:17]
	v_exp_f32_e32 v230, v50
	v_exp_f32_e32 v51, v51
	v_exp_f32_e32 v231, v52
	v_exp_f32_e32 v52, v53
	v_add_f32_e32 v229, v230, v229
	v_exp_f32_e32 v53, v54
	v_add_f32_e32 v229, v51, v229
	v_exp_f32_e32 v54, v55
	v_add_f32_e32 v50, v231, v229
	v_exp_f32_e32 v55, v56
	ds_read_b128 v[42:45], v228 offset:18496
	ds_read_b128 v[46:49], v228 offset:23104
	v_add_f32_e32 v50, v52, v50
	v_exp_f32_e32 v41, v57
	v_add_f32_e32 v50, v53, v50
	v_add_f32_e32 v50, v54, v50
	v_add_f32_e32 v50, v55, v50
	v_add_f32_e32 v56, v41, v50
	v_cvt_pk_bf16_f32 v50, v230, v51
	v_cvt_pk_bf16_f32 v51, v231, v52
	v_cvt_pk_bf16_f32 v52, v53, v54
	v_cvt_pk_bf16_f32 v53, v55, v41
	s_waitcnt lgkmcnt(1)
	s_nop 0
	v_mfma_f32_32x32x16_bf16 v[18:33], v[42:45], v[50:53], v[18:33]
	s_waitcnt lgkmcnt(0)
	v_mfma_f32_32x32x16_bf16 v[2:17], v[46:49], v[50:53], v[2:17]
	v_exp_f32_e32 v38, v58
	v_exp_f32_e32 v34, v59
	v_exp_f32_e32 v0, v60
	v_exp_f32_e32 v35, v61
	v_add_f32_e32 v41, v38, v56
	v_exp_f32_e32 v36, v62
	ds_read_b128 v[42:45], v228 offset:18528
	ds_read_b128 v[46:49], v228 offset:23136
	v_add_f32_e32 v41, v34, v41
	v_exp_f32_e32 v37, v63
	v_exp_f32_e32 v39, v64
	v_exp_f32_e32 v40, v65
	v_add_f32_e32 v41, v0, v41
	v_add_f32_e32 v41, v35, v41
	v_add_f32_e32 v41, v36, v41
	v_add_f32_e32 v41, v37, v41
	v_cvt_pk_bf16_f32 v34, v38, v34
	v_cvt_pk_bf16_f32 v35, v0, v35
	v_cvt_pk_bf16_f32 v36, v36, v37
	v_cvt_pk_bf16_f32 v37, v39, v40
	v_add_f32_e32 v41, v39, v41
	v_add_f32_e32 v41, v40, v41
	s_waitcnt lgkmcnt(1)
	v_mfma_f32_32x32x16_bf16 v[18:33], v[42:45], v[34:37], v[18:33]
	s_waitcnt lgkmcnt(0)
	v_mfma_f32_32x32x16_bf16 v[2:17], v[46:49], v[34:37], v[2:17]
	v_add_f32_e32 v100, v100, v41
	s_branch .LBB0_618

; DI float max3_asm(float a, float b, float c) { float r; asm("v_max3_f32 %0, %1, %2, %3" : "=v"(r) : "v"(a), "v"(b), "v"(c)); return r; }
; template <bool MASK>
; DI float mask_rowmax(f32x16& s0, f32x16& s1, const TP& tp) {
;     ...
;     const float seed = __builtin_fminf(s0[15], s1[15]);
;     float ma = seed, mb = seed;
; #pragma unroll
;     for (int r = 0; r < 16; r += 2) { ma = max3_asm(ma, s0[r], s1[r]); mb = max3_asm(mb, s0[r + 1], s1[r + 1]); }
;     const float mx = fmaxf(ma, mb);
;     return fmaxf(mx, __shfl_xor(mx, 32));
; }
; template <int MODE, bool MASK, bool WITH_O>
; DI void attn_tile_t(lptr Kt, lptr Vt, const bf16x8 (&qf)[4], f32x16& o0, f32x16& o1, RowState& rs, const TP& tp, int lane) {
;     const int hi = lane >> 5;
;     f32x16 s0, s1;
;     bias_init<MODE>(s0, s1, tp, tp.fb - rs.mref, hi);
;     qk_acc(Kt, qf, s0, s1, lane);
;     const float mx = mask_rowmax<MASK>(s0, s1, tp);
;     const bool was = rs.seen; rs.seen = was || (mx > -1e29f);
;     const bool trig = (mx > 8.f) || (!was && mx > -1e29f && mx < -8.f);
.Lslc_join:
	v_max_f32_e32 v49, v40, v40
	v_max_f32_e32 v57, v48, v48
	v_min_f32_e32 v49, v57, v49
	v_max3_f32 v57, v49, v106, v102
	v_max3_f32 v49, v49, v103, v51
	s_mov_b32 s0, 0xefa18f08
	v_max3_f32 v57, v57, v104, v50
	v_max3_f32 v49, v49, v105, v52
	v_max3_f32 v57, v57, v107, v53
	v_max3_f32 v49, v49, v108, v54
	v_max3_f32 v57, v57, v109, v55
	v_max3_f32 v49, v49, v110, v41
	v_max3_f32 v57, v57, v56, v38
	v_max3_f32 v49, v49, v43, v34
	v_max3_f32 v57, v57, v42, v0
	v_max3_f32 v49, v49, v44, v35
	v_max3_f32 v57, v57, v45, v36
	v_max3_f32 v49, v49, v46, v37
	v_max3_f32 v57, v57, v47, v39
	v_max3_f32 v49, v49, v48, v40
	v_max_f32_e32 v49, v49, v49
	v_max_f32_e32 v57, v57, v57
	v_max_f32_e32 v49, v57, v49
	v_mov_b32_e32 v57, v49
	s_nop 1
	v_permlane32_swap_b32_e32 v57, v49
	s_waitcnt lgkmcnt(0)
	v_max_f32_e32 v49, v49, v57
	v_cmp_lt_f32_e64 s[28:29], s0, v49
	s_mov_b32 s0, 0x41000000
	v_cmp_lt_f32_e32 vcc, s0, v49
	s_mov_b32 s0, 0xc1000000
	v_cmp_gt_f32_e64 s[0:1], s0, v49
	s_and_b64 s[0:1], s[0:1], s[28:29]
	s_andn2_b64 s[0:1], s[0:1], s[22:23]
	s_or_b64 s[0:1], s[0:1], vcc
	s_and_b64 vcc, exec, s[0:1]
	s_cbranch_vccnz .LBB0_622
